# v9 + hand-written R1 row pass (straight-line 8 rows per wave, x rows prefetched two rows ahead, params loaded once per mod row)
# baseline (speedup 1.0000x reference)
.LBB0_172:
	s_cmp_lt_i32 s96, 2
	s_cselect_b64 s[4:5], -1, 0
	s_lshl_b32 s54, s2, 3
	s_and_b64 s[4:5], s[4:5], s[0:1]
	s_add_i32 s44, s89, s54
	s_andn2_b64 vcc, exec, s[4:5]
	s_lshl_b32 s48, s33, 4
	s_cbranch_vccnz .LBB0_181
	s_cmpk_gt_i32 s44, 0x1fff
	s_cbranch_scc1 .LBB0_181
	s_mov_b32 s34, s89
	v_readlane_b32 s6, v254, 6
	v_readlane_b32 s7, v254, 7
	v_readlane_b32 s8, v254, 8
	v_readlane_b32 s9, v254, 9
	v_readlane_b32 s10, v254, 20
	v_readlane_b32 s11, v254, 21
	v_lshlrev_b32_e32 v230, 5, v191
	v_lshlrev_b32_e32 v231, 4, v191
	v_mov_b32_e32 v246, 0x3a000000
	s_nop 1
	s_lshl_b32 s12, s44, 1
	s_lshl_b32 s13, s12, 13
	s_add_u32 s14, s6, s13
	s_addc_u32 s15, s7, 0
	s_add_u32 s16, s8, s13
	s_addc_u32 s17, s9, 0
	s_and_b32 s18, s12, 1023
	s_lshr_b32 s19, s12, 10
	s_add_u32 s20, s10, 0x1000
	s_addc_u32 s21, s11, 0
	s_lshl_b32 s22, s12, 12
	s_add_u32 s22, s22, 0x4800000
	s_add_u32 s22, s62, s22
	s_addc_u32 s23, s63, 0
	global_load_dwordx4 v[130:133], v230, s[10:11]
	global_load_dwordx4 v[134:137], v230, s[10:11] offset:16
	global_load_dwordx4 v[138:141], v230, s[10:11] offset:2048
	global_load_dwordx4 v[142:145], v230, s[10:11] offset:2064
	global_load_dwordx4 v[146:149], v230, s[20:21]
	global_load_dwordx4 v[150:153], v230, s[20:21] offset:16
	global_load_dwordx4 v[154:157], v230, s[20:21] offset:2048
	global_load_dwordx4 v[158:161], v230, s[20:21] offset:2064
	s_add_u32 s26, s14, 0
	s_addc_u32 s27, s15, 0
	s_add_u32 s24, s26, 0x1000
	s_addc_u32 s25, s27, 0
	global_load_dwordx4 v[2:5], v230, s[26:27] nt
	global_load_dwordx4 v[6:9], v230, s[26:27] offset:16 nt
	global_load_dwordx4 v[10:13], v230, s[26:27] offset:2048 nt
	global_load_dwordx4 v[14:17], v230, s[26:27] offset:2064 nt
	global_load_dwordx4 v[18:21], v230, s[24:25] nt
	global_load_dwordx4 v[22:25], v230, s[24:25] offset:16 nt
	global_load_dwordx4 v[26:29], v230, s[24:25] offset:2048 nt
	global_load_dwordx4 v[30:33], v230, s[24:25] offset:2064 nt
	s_mov_b32 s38, 0
	s_add_u32 s38, s62, s38
	s_addc_u32 s39, s63, 0
	s_add_u32 s40, s38, 0x2000
	s_addc_u32 s41, s39, 0
	s_add_u32 s64, s38, 0x1000
	s_addc_u32 s65, s39, 0
	s_add_u32 s66, s40, 0x1000
	s_addc_u32 s67, s41, 0
	global_load_dwordx4 v[194:197], v230, s[38:39]
	global_load_dwordx4 v[162:165], v230, s[40:41]
	global_load_dwordx4 v[198:201], v230, s[38:39] offset:16
	global_load_dwordx4 v[166:169], v230, s[40:41] offset:16
	global_load_dwordx4 v[202:205], v230, s[38:39] offset:2048
	global_load_dwordx4 v[170:173], v230, s[40:41] offset:2048
	global_load_dwordx4 v[206:209], v230, s[38:39] offset:2064
	global_load_dwordx4 v[174:177], v230, s[40:41] offset:2064
	global_load_dwordx4 v[210:213], v230, s[64:65]
	global_load_dwordx4 v[178:181], v230, s[66:67]
	global_load_dwordx4 v[214:217], v230, s[64:65] offset:16
	global_load_dwordx4 v[182:185], v230, s[66:67] offset:16
	global_load_dwordx4 v[218:221], v230, s[64:65] offset:2048
	global_load_dwordx4 v[186:189], v230, s[66:67] offset:2048
	global_load_dwordx4 v[222:225], v230, s[64:65] offset:2064
	global_load_dwordx4 v[226:229], v230, s[66:67] offset:2064
	s_add_u32 s26, s14, 8192
	s_addc_u32 s27, s15, 0
	s_add_u32 s24, s26, 0x1000
	s_addc_u32 s25, s27, 0
	global_load_dwordx4 v[34:37], v230, s[26:27] nt
	global_load_dwordx4 v[38:41], v230, s[26:27] offset:16 nt
	global_load_dwordx4 v[42:45], v230, s[26:27] offset:2048 nt
	global_load_dwordx4 v[46:49], v230, s[26:27] offset:2064 nt
	global_load_dwordx4 v[50:53], v230, s[24:25] nt
	global_load_dwordx4 v[54:57], v230, s[24:25] offset:16 nt
	global_load_dwordx4 v[58:61], v230, s[24:25] offset:2048 nt
	global_load_dwordx4 v[62:65], v230, s[24:25] offset:2064 nt
	s_add_u32 s26, s14, 33554432
	s_addc_u32 s27, s15, 0
	s_add_u32 s24, s26, 0x1000
	s_addc_u32 s25, s27, 0
	global_load_dwordx4 v[66:69], v230, s[26:27] nt
	global_load_dwordx4 v[70:73], v230, s[26:27] offset:16 nt
	global_load_dwordx4 v[74:77], v230, s[26:27] offset:2048 nt
	global_load_dwordx4 v[78:81], v230, s[26:27] offset:2064 nt
	global_load_dwordx4 v[82:85], v230, s[24:25] nt
	global_load_dwordx4 v[86:89], v230, s[24:25] offset:16 nt
	global_load_dwordx4 v[90:93], v230, s[24:25] offset:2048 nt
	global_load_dwordx4 v[94:97], v230, s[24:25] offset:2064 nt
	s_waitcnt vmcnt(32)
	v_pk_mul_f32 v[232:233], v[2:3], v[2:3]
	v_pk_fma_f32 v[232:233], v[4:5], v[4:5], v[232:233]
	v_pk_fma_f32 v[232:233], v[6:7], v[6:7], v[232:233]
	v_pk_fma_f32 v[232:233], v[8:9], v[8:9], v[232:233]
	v_pk_fma_f32 v[232:233], v[10:11], v[10:11], v[232:233]
	v_pk_fma_f32 v[232:233], v[12:13], v[12:13], v[232:233]
	v_pk_fma_f32 v[232:233], v[14:15], v[14:15], v[232:233]
	v_pk_fma_f32 v[232:233], v[16:17], v[16:17], v[232:233]
	v_pk_fma_f32 v[232:233], v[18:19], v[18:19], v[232:233]
	v_pk_fma_f32 v[232:233], v[20:21], v[20:21], v[232:233]
	v_pk_fma_f32 v[232:233], v[22:23], v[22:23], v[232:233]
	v_pk_fma_f32 v[232:233], v[24:25], v[24:25], v[232:233]
	v_pk_fma_f32 v[232:233], v[26:27], v[26:27], v[232:233]
	v_pk_fma_f32 v[232:233], v[28:29], v[28:29], v[232:233]
	v_pk_fma_f32 v[232:233], v[30:31], v[30:31], v[232:233]
	v_pk_fma_f32 v[232:233], v[32:33], v[32:33], v[232:233]
	v_add_f32_e32 v232, v232, v233
	s_nop 1
	v_add_f32_dpp v232, v232, v232 quad_perm:[1,0,3,2] row_mask:0xf bank_mask:0xf
	s_nop 1
	v_add_f32_dpp v232, v232, v232 quad_perm:[2,3,0,1] row_mask:0xf bank_mask:0xf
	s_nop 1
	v_add_f32_dpp v232, v232, v232 row_half_mirror row_mask:0xf bank_mask:0xf
	s_nop 1
	v_add_f32_dpp v232, v232, v232 row_mirror row_mask:0xf bank_mask:0xf
	s_nop 1
	v_readlane_b32 s0, v232, 0
	v_readlane_b32 s1, v232, 16
	v_readlane_b32 s68, v232, 32
	v_readlane_b32 s69, v232, 48
	s_nop 3
	v_mov_b32_e32 v234, s0
	v_add_f32_e32 v234, s1, v234
	v_add_f32_e32 v234, s68, v234
	v_add_f32_e32 v234, s69, v234
	v_fmaak_f32 v234, v234, v246, 0x358637bd
	v_rsq_f32_e32 v234, v234
	s_nop 0
	v_mov_b32_e32 v235, v234
	s_waitcnt vmcnt(16)
	v_pk_add_f32 v[162:163], v[162:163], 1.0 op_sel_hi:[1,0]
	v_pk_add_f32 v[164:165], v[164:165], 1.0 op_sel_hi:[1,0]
	v_pk_add_f32 v[166:167], v[166:167], 1.0 op_sel_hi:[1,0]
	v_pk_add_f32 v[168:169], v[168:169], 1.0 op_sel_hi:[1,0]
	v_pk_add_f32 v[170:171], v[170:171], 1.0 op_sel_hi:[1,0]
	v_pk_add_f32 v[172:173], v[172:173], 1.0 op_sel_hi:[1,0]
	v_pk_add_f32 v[174:175], v[174:175], 1.0 op_sel_hi:[1,0]
	v_pk_add_f32 v[176:177], v[176:177], 1.0 op_sel_hi:[1,0]
	v_pk_add_f32 v[178:179], v[178:179], 1.0 op_sel_hi:[1,0]
	v_pk_add_f32 v[180:181], v[180:181], 1.0 op_sel_hi:[1,0]
	v_pk_add_f32 v[182:183], v[182:183], 1.0 op_sel_hi:[1,0]
	v_pk_add_f32 v[184:185], v[184:185], 1.0 op_sel_hi:[1,0]
	v_pk_add_f32 v[186:187], v[186:187], 1.0 op_sel_hi:[1,0]
	v_pk_add_f32 v[188:189], v[188:189], 1.0 op_sel_hi:[1,0]
	v_pk_add_f32 v[226:227], v[226:227], 1.0 op_sel_hi:[1,0]
	v_pk_add_f32 v[228:229], v[228:229], 1.0 op_sel_hi:[1,0]
	s_add_u32 s70, s22, 0
	s_addc_u32 s71, s23, 0
	v_pk_mul_f32 v[238:239], v[2:3], v[234:235]
	v_pk_mul_f32 v[240:241], v[4:5], v[234:235]
	v_pk_mul_f32 v[238:239], v[130:131], v[238:239]
	v_pk_mul_f32 v[240:241], v[132:133], v[240:241]
	v_pk_fma_f32 v[238:239], v[238:239], v[162:163], v[194:195]
	v_pk_fma_f32 v[240:241], v[240:241], v[164:165], v[196:197]
	v_cvt_pk_bf16_f32 v248, v238, v239
	v_cvt_pk_bf16_f32 v249, v240, v241
	v_pk_mul_f32 v[242:243], v[6:7], v[234:235]
	v_pk_mul_f32 v[244:245], v[8:9], v[234:235]
	v_pk_mul_f32 v[242:243], v[134:135], v[242:243]
	v_pk_mul_f32 v[244:245], v[136:137], v[244:245]
	v_pk_fma_f32 v[242:243], v[242:243], v[166:167], v[198:199]
	v_pk_fma_f32 v[244:245], v[244:245], v[168:169], v[200:201]
	v_cvt_pk_bf16_f32 v250, v242, v243
	v_cvt_pk_bf16_f32 v251, v244, v245
	global_store_dwordx4 v231, v[248:251], s[70:71]
	s_nop 1
	v_pk_mul_f32 v[238:239], v[10:11], v[234:235]
	v_pk_mul_f32 v[240:241], v[12:13], v[234:235]
	v_pk_mul_f32 v[238:239], v[138:139], v[238:239]
	v_pk_mul_f32 v[240:241], v[140:141], v[240:241]
	v_pk_fma_f32 v[238:239], v[238:239], v[170:171], v[202:203]
	v_pk_fma_f32 v[240:241], v[240:241], v[172:173], v[204:205]
	v_cvt_pk_bf16_f32 v248, v238, v239
	v_cvt_pk_bf16_f32 v249, v240, v241
	v_pk_mul_f32 v[242:243], v[14:15], v[234:235]
	v_pk_mul_f32 v[244:245], v[16:17], v[234:235]
	v_pk_mul_f32 v[242:243], v[142:143], v[242:243]
	v_pk_mul_f32 v[244:245], v[144:145], v[244:245]
	v_pk_fma_f32 v[242:243], v[242:243], v[174:175], v[206:207]
	v_pk_fma_f32 v[244:245], v[244:245], v[176:177], v[208:209]
	v_cvt_pk_bf16_f32 v250, v242, v243
	v_cvt_pk_bf16_f32 v251, v244, v245
	global_store_dwordx4 v231, v[248:251], s[70:71] offset:1024
	s_nop 1
	v_pk_mul_f32 v[238:239], v[18:19], v[234:235]
	v_pk_mul_f32 v[240:241], v[20:21], v[234:235]
	v_pk_mul_f32 v[238:239], v[146:147], v[238:239]
	v_pk_mul_f32 v[240:241], v[148:149], v[240:241]
	v_pk_fma_f32 v[238:239], v[238:239], v[178:179], v[210:211]
	v_pk_fma_f32 v[240:241], v[240:241], v[180:181], v[212:213]
	v_cvt_pk_bf16_f32 v248, v238, v239
	v_cvt_pk_bf16_f32 v249, v240, v241
	v_pk_mul_f32 v[242:243], v[22:23], v[234:235]
	v_pk_mul_f32 v[244:245], v[24:25], v[234:235]
	v_pk_mul_f32 v[242:243], v[150:151], v[242:243]
	v_pk_mul_f32 v[244:245], v[152:153], v[244:245]
	v_pk_fma_f32 v[242:243], v[242:243], v[182:183], v[214:215]
	v_pk_fma_f32 v[244:245], v[244:245], v[184:185], v[216:217]
	v_cvt_pk_bf16_f32 v250, v242, v243
	v_cvt_pk_bf16_f32 v251, v244, v245
	global_store_dwordx4 v231, v[248:251], s[70:71] offset:2048
	s_nop 1
	v_pk_mul_f32 v[238:239], v[26:27], v[234:235]
	v_pk_mul_f32 v[240:241], v[28:29], v[234:235]
	v_pk_mul_f32 v[238:239], v[154:155], v[238:239]
	v_pk_mul_f32 v[240:241], v[156:157], v[240:241]
	v_pk_fma_f32 v[238:239], v[238:239], v[186:187], v[218:219]
	v_pk_fma_f32 v[240:241], v[240:241], v[188:189], v[220:221]
	v_cvt_pk_bf16_f32 v248, v238, v239
	v_cvt_pk_bf16_f32 v249, v240, v241
	v_pk_mul_f32 v[242:243], v[30:31], v[234:235]
	v_pk_mul_f32 v[244:245], v[32:33], v[234:235]
	v_pk_mul_f32 v[242:243], v[158:159], v[242:243]
	v_pk_mul_f32 v[244:245], v[160:161], v[244:245]
	v_pk_fma_f32 v[242:243], v[242:243], v[226:227], v[222:223]
	v_pk_fma_f32 v[244:245], v[244:245], v[228:229], v[224:225]
	v_cvt_pk_bf16_f32 v250, v242, v243
	v_cvt_pk_bf16_f32 v251, v244, v245
	global_store_dwordx4 v231, v[248:251], s[70:71] offset:3072
	s_nop 1
	s_add_u32 s26, s14, 33562624
	s_addc_u32 s27, s15, 0
	s_add_u32 s24, s26, 0x1000
	s_addc_u32 s25, s27, 0
	global_load_dwordx4 v[2:5], v230, s[26:27] nt
	global_load_dwordx4 v[6:9], v230, s[26:27] offset:16 nt
	global_load_dwordx4 v[10:13], v230, s[26:27] offset:2048 nt
	global_load_dwordx4 v[14:17], v230, s[26:27] offset:2064 nt
	global_load_dwordx4 v[18:21], v230, s[24:25] nt
	global_load_dwordx4 v[22:25], v230, s[24:25] offset:16 nt
	global_load_dwordx4 v[26:29], v230, s[24:25] offset:2048 nt
	global_load_dwordx4 v[30:33], v230, s[24:25] offset:2064 nt
	s_waitcnt vmcnt(20)
	v_pk_mul_f32 v[232:233], v[34:35], v[34:35]
	v_pk_fma_f32 v[232:233], v[36:37], v[36:37], v[232:233]
	v_pk_fma_f32 v[232:233], v[38:39], v[38:39], v[232:233]
	v_pk_fma_f32 v[232:233], v[40:41], v[40:41], v[232:233]
	v_pk_fma_f32 v[232:233], v[42:43], v[42:43], v[232:233]
	v_pk_fma_f32 v[232:233], v[44:45], v[44:45], v[232:233]
	v_pk_fma_f32 v[232:233], v[46:47], v[46:47], v[232:233]
	v_pk_fma_f32 v[232:233], v[48:49], v[48:49], v[232:233]
	v_pk_fma_f32 v[232:233], v[50:51], v[50:51], v[232:233]
	v_pk_fma_f32 v[232:233], v[52:53], v[52:53], v[232:233]
	v_pk_fma_f32 v[232:233], v[54:55], v[54:55], v[232:233]
	v_pk_fma_f32 v[232:233], v[56:57], v[56:57], v[232:233]
	v_pk_fma_f32 v[232:233], v[58:59], v[58:59], v[232:233]
	v_pk_fma_f32 v[232:233], v[60:61], v[60:61], v[232:233]
	v_pk_fma_f32 v[232:233], v[62:63], v[62:63], v[232:233]
	v_pk_fma_f32 v[232:233], v[64:65], v[64:65], v[232:233]
	v_add_f32_e32 v232, v232, v233
	s_nop 1
	v_add_f32_dpp v232, v232, v232 quad_perm:[1,0,3,2] row_mask:0xf bank_mask:0xf
	s_nop 1
	v_add_f32_dpp v232, v232, v232 quad_perm:[2,3,0,1] row_mask:0xf bank_mask:0xf
	s_nop 1
	v_add_f32_dpp v232, v232, v232 row_half_mirror row_mask:0xf bank_mask:0xf
	s_nop 1
	v_add_f32_dpp v232, v232, v232 row_mirror row_mask:0xf bank_mask:0xf
	s_nop 1
	v_readlane_b32 s0, v232, 0
	v_readlane_b32 s1, v232, 16
	v_readlane_b32 s68, v232, 32
	v_readlane_b32 s69, v232, 48
	s_nop 3
	v_mov_b32_e32 v234, s0
	v_add_f32_e32 v234, s1, v234
	v_add_f32_e32 v234, s68, v234
	v_add_f32_e32 v234, s69, v234
	v_fmaak_f32 v234, v234, v246, 0x358637bd
	v_rsq_f32_e32 v234, v234
	s_nop 0
	v_mov_b32_e32 v235, v234
	s_add_u32 s70, s22, 4096
	s_addc_u32 s71, s23, 0
	v_pk_mul_f32 v[238:239], v[34:35], v[234:235]
	v_pk_mul_f32 v[240:241], v[36:37], v[234:235]
	v_pk_mul_f32 v[238:239], v[130:131], v[238:239]
	v_pk_mul_f32 v[240:241], v[132:133], v[240:241]
	v_pk_fma_f32 v[238:239], v[238:239], v[162:163], v[194:195]
	v_pk_fma_f32 v[240:241], v[240:241], v[164:165], v[196:197]
	v_cvt_pk_bf16_f32 v248, v238, v239
	v_cvt_pk_bf16_f32 v249, v240, v241
	v_pk_mul_f32 v[242:243], v[38:39], v[234:235]
	v_pk_mul_f32 v[244:245], v[40:41], v[234:235]
	v_pk_mul_f32 v[242:243], v[134:135], v[242:243]
	v_pk_mul_f32 v[244:245], v[136:137], v[244:245]
	v_pk_fma_f32 v[242:243], v[242:243], v[166:167], v[198:199]
	v_pk_fma_f32 v[244:245], v[244:245], v[168:169], v[200:201]
	v_cvt_pk_bf16_f32 v250, v242, v243
	v_cvt_pk_bf16_f32 v251, v244, v245
	global_store_dwordx4 v231, v[248:251], s[70:71]
	s_nop 1
	v_pk_mul_f32 v[238:239], v[42:43], v[234:235]
	v_pk_mul_f32 v[240:241], v[44:45], v[234:235]
	v_pk_mul_f32 v[238:239], v[138:139], v[238:239]
	v_pk_mul_f32 v[240:241], v[140:141], v[240:241]
	v_pk_fma_f32 v[238:239], v[238:239], v[170:171], v[202:203]
	v_pk_fma_f32 v[240:241], v[240:241], v[172:173], v[204:205]
	v_cvt_pk_bf16_f32 v248, v238, v239
	v_cvt_pk_bf16_f32 v249, v240, v241
	v_pk_mul_f32 v[242:243], v[46:47], v[234:235]
	v_pk_mul_f32 v[244:245], v[48:49], v[234:235]
	v_pk_mul_f32 v[242:243], v[142:143], v[242:243]
	v_pk_mul_f32 v[244:245], v[144:145], v[244:245]
	v_pk_fma_f32 v[242:243], v[242:243], v[174:175], v[206:207]
	v_pk_fma_f32 v[244:245], v[244:245], v[176:177], v[208:209]
	v_cvt_pk_bf16_f32 v250, v242, v243
	v_cvt_pk_bf16_f32 v251, v244, v245
	global_store_dwordx4 v231, v[248:251], s[70:71] offset:1024
	s_nop 1
	v_pk_mul_f32 v[238:239], v[50:51], v[234:235]
	v_pk_mul_f32 v[240:241], v[52:53], v[234:235]
	v_pk_mul_f32 v[238:239], v[146:147], v[238:239]
	v_pk_mul_f32 v[240:241], v[148:149], v[240:241]
	v_pk_fma_f32 v[238:239], v[238:239], v[178:179], v[210:211]
	v_pk_fma_f32 v[240:241], v[240:241], v[180:181], v[212:213]
	v_cvt_pk_bf16_f32 v248, v238, v239
	v_cvt_pk_bf16_f32 v249, v240, v241
	v_pk_mul_f32 v[242:243], v[54:55], v[234:235]
	v_pk_mul_f32 v[244:245], v[56:57], v[234:235]
	v_pk_mul_f32 v[242:243], v[150:151], v[242:243]
	v_pk_mul_f32 v[244:245], v[152:153], v[244:245]
	v_pk_fma_f32 v[242:243], v[242:243], v[182:183], v[214:215]
	v_pk_fma_f32 v[244:245], v[244:245], v[184:185], v[216:217]
	v_cvt_pk_bf16_f32 v250, v242, v243
	v_cvt_pk_bf16_f32 v251, v244, v245
	global_store_dwordx4 v231, v[248:251], s[70:71] offset:2048
	s_nop 1
	v_pk_mul_f32 v[238:239], v[58:59], v[234:235]
	v_pk_mul_f32 v[240:241], v[60:61], v[234:235]
	v_pk_mul_f32 v[238:239], v[154:155], v[238:239]
	v_pk_mul_f32 v[240:241], v[156:157], v[240:241]
	v_pk_fma_f32 v[238:239], v[238:239], v[186:187], v[218:219]
	v_pk_fma_f32 v[240:241], v[240:241], v[188:189], v[220:221]
	v_cvt_pk_bf16_f32 v248, v238, v239
	v_cvt_pk_bf16_f32 v249, v240, v241
	v_pk_mul_f32 v[242:243], v[62:63], v[234:235]
	v_pk_mul_f32 v[244:245], v[64:65], v[234:235]
	v_pk_mul_f32 v[242:243], v[158:159], v[242:243]
	v_pk_mul_f32 v[244:245], v[160:161], v[244:245]
	v_pk_fma_f32 v[242:243], v[242:243], v[226:227], v[222:223]
	v_pk_fma_f32 v[244:245], v[244:245], v[228:229], v[224:225]
	v_cvt_pk_bf16_f32 v250, v242, v243
	v_cvt_pk_bf16_f32 v251, v244, v245
	global_store_dwordx4 v231, v[248:251], s[70:71] offset:3072
	s_nop 1
	s_add_u32 s26, s16, 0
	s_addc_u32 s27, s17, 0
	s_add_u32 s24, s26, 0x1000
	s_addc_u32 s25, s27, 0
	global_load_dwordx4 v[34:37], v230, s[26:27] nt
	global_load_dwordx4 v[38:41], v230, s[26:27] offset:16 nt
	global_load_dwordx4 v[42:45], v230, s[26:27] offset:2048 nt
	global_load_dwordx4 v[46:49], v230, s[26:27] offset:2064 nt
	global_load_dwordx4 v[50:53], v230, s[24:25] nt
	global_load_dwordx4 v[54:57], v230, s[24:25] offset:16 nt
	global_load_dwordx4 v[58:61], v230, s[24:25] offset:2048 nt
	global_load_dwordx4 v[62:65], v230, s[24:25] offset:2064 nt
	s_waitcnt vmcnt(24)
	v_pk_mul_f32 v[232:233], v[66:67], v[66:67]
	v_pk_fma_f32 v[232:233], v[68:69], v[68:69], v[232:233]
	v_pk_fma_f32 v[232:233], v[70:71], v[70:71], v[232:233]
	v_pk_fma_f32 v[232:233], v[72:73], v[72:73], v[232:233]
	v_pk_fma_f32 v[232:233], v[74:75], v[74:75], v[232:233]
	v_pk_fma_f32 v[232:233], v[76:77], v[76:77], v[232:233]
	v_pk_fma_f32 v[232:233], v[78:79], v[78:79], v[232:233]
	v_pk_fma_f32 v[232:233], v[80:81], v[80:81], v[232:233]
	v_pk_fma_f32 v[232:233], v[82:83], v[82:83], v[232:233]
	v_pk_fma_f32 v[232:233], v[84:85], v[84:85], v[232:233]
	v_pk_fma_f32 v[232:233], v[86:87], v[86:87], v[232:233]
	v_pk_fma_f32 v[232:233], v[88:89], v[88:89], v[232:233]
	v_pk_fma_f32 v[232:233], v[90:91], v[90:91], v[232:233]
	v_pk_fma_f32 v[232:233], v[92:93], v[92:93], v[232:233]
	v_pk_fma_f32 v[232:233], v[94:95], v[94:95], v[232:233]
	v_pk_fma_f32 v[232:233], v[96:97], v[96:97], v[232:233]
	v_add_f32_e32 v232, v232, v233
	s_nop 1
	v_add_f32_dpp v232, v232, v232 quad_perm:[1,0,3,2] row_mask:0xf bank_mask:0xf
	s_nop 1
	v_add_f32_dpp v232, v232, v232 quad_perm:[2,3,0,1] row_mask:0xf bank_mask:0xf
	s_nop 1
	v_add_f32_dpp v232, v232, v232 row_half_mirror row_mask:0xf bank_mask:0xf
	s_nop 1
	v_add_f32_dpp v232, v232, v232 row_mirror row_mask:0xf bank_mask:0xf
	s_nop 1
	v_readlane_b32 s0, v232, 0
	v_readlane_b32 s1, v232, 16
	v_readlane_b32 s68, v232, 32
	v_readlane_b32 s69, v232, 48
	s_nop 3
	v_mov_b32_e32 v234, s0
	v_add_f32_e32 v234, s1, v234
	v_add_f32_e32 v234, s68, v234
	v_add_f32_e32 v234, s69, v234
	v_fmaak_f32 v234, v234, v246, 0x358637bd
	v_rsq_f32_e32 v234, v234
	s_nop 0
	v_mov_b32_e32 v235, v234
	s_add_u32 s70, s22, 16777216
	s_addc_u32 s71, s23, 0
	v_pk_mul_f32 v[238:239], v[66:67], v[234:235]
	v_pk_mul_f32 v[240:241], v[68:69], v[234:235]
	v_pk_mul_f32 v[238:239], v[130:131], v[238:239]
	v_pk_mul_f32 v[240:241], v[132:133], v[240:241]
	v_pk_fma_f32 v[238:239], v[238:239], v[162:163], v[194:195]
	v_pk_fma_f32 v[240:241], v[240:241], v[164:165], v[196:197]
	v_cvt_pk_bf16_f32 v248, v238, v239
	v_cvt_pk_bf16_f32 v249, v240, v241
	v_pk_mul_f32 v[242:243], v[70:71], v[234:235]
	v_pk_mul_f32 v[244:245], v[72:73], v[234:235]
	v_pk_mul_f32 v[242:243], v[134:135], v[242:243]
	v_pk_mul_f32 v[244:245], v[136:137], v[244:245]
	v_pk_fma_f32 v[242:243], v[242:243], v[166:167], v[198:199]
	v_pk_fma_f32 v[244:245], v[244:245], v[168:169], v[200:201]
	v_cvt_pk_bf16_f32 v250, v242, v243
	v_cvt_pk_bf16_f32 v251, v244, v245
	global_store_dwordx4 v231, v[248:251], s[70:71]
	s_nop 1
	v_pk_mul_f32 v[238:239], v[74:75], v[234:235]
	v_pk_mul_f32 v[240:241], v[76:77], v[234:235]
	v_pk_mul_f32 v[238:239], v[138:139], v[238:239]
	v_pk_mul_f32 v[240:241], v[140:141], v[240:241]
	v_pk_fma_f32 v[238:239], v[238:239], v[170:171], v[202:203]
	v_pk_fma_f32 v[240:241], v[240:241], v[172:173], v[204:205]
	v_cvt_pk_bf16_f32 v248, v238, v239
	v_cvt_pk_bf16_f32 v249, v240, v241
	v_pk_mul_f32 v[242:243], v[78:79], v[234:235]
	v_pk_mul_f32 v[244:245], v[80:81], v[234:235]
	v_pk_mul_f32 v[242:243], v[142:143], v[242:243]
	v_pk_mul_f32 v[244:245], v[144:145], v[244:245]
	v_pk_fma_f32 v[242:243], v[242:243], v[174:175], v[206:207]
	v_pk_fma_f32 v[244:245], v[244:245], v[176:177], v[208:209]
	v_cvt_pk_bf16_f32 v250, v242, v243
	v_cvt_pk_bf16_f32 v251, v244, v245
	global_store_dwordx4 v231, v[248:251], s[70:71] offset:1024
	s_nop 1
	v_pk_mul_f32 v[238:239], v[82:83], v[234:235]
	v_pk_mul_f32 v[240:241], v[84:85], v[234:235]
	v_pk_mul_f32 v[238:239], v[146:147], v[238:239]
	v_pk_mul_f32 v[240:241], v[148:149], v[240:241]
	v_pk_fma_f32 v[238:239], v[238:239], v[178:179], v[210:211]
	v_pk_fma_f32 v[240:241], v[240:241], v[180:181], v[212:213]
	v_cvt_pk_bf16_f32 v248, v238, v239
	v_cvt_pk_bf16_f32 v249, v240, v241
	v_pk_mul_f32 v[242:243], v[86:87], v[234:235]
	v_pk_mul_f32 v[244:245], v[88:89], v[234:235]
	v_pk_mul_f32 v[242:243], v[150:151], v[242:243]
	v_pk_mul_f32 v[244:245], v[152:153], v[244:245]
	v_pk_fma_f32 v[242:243], v[242:243], v[182:183], v[214:215]
	v_pk_fma_f32 v[244:245], v[244:245], v[184:185], v[216:217]
	v_cvt_pk_bf16_f32 v250, v242, v243
	v_cvt_pk_bf16_f32 v251, v244, v245
	global_store_dwordx4 v231, v[248:251], s[70:71] offset:2048
	s_nop 1
	v_pk_mul_f32 v[238:239], v[90:91], v[234:235]
	v_pk_mul_f32 v[240:241], v[92:93], v[234:235]
	v_pk_mul_f32 v[238:239], v[154:155], v[238:239]
	v_pk_mul_f32 v[240:241], v[156:157], v[240:241]
	v_pk_fma_f32 v[238:239], v[238:239], v[186:187], v[218:219]
	v_pk_fma_f32 v[240:241], v[240:241], v[188:189], v[220:221]
	v_cvt_pk_bf16_f32 v248, v238, v239
	v_cvt_pk_bf16_f32 v249, v240, v241
	v_pk_mul_f32 v[242:243], v[94:95], v[234:235]
	v_pk_mul_f32 v[244:245], v[96:97], v[234:235]
	v_pk_mul_f32 v[242:243], v[158:159], v[242:243]
	v_pk_mul_f32 v[244:245], v[160:161], v[244:245]
	v_pk_fma_f32 v[242:243], v[242:243], v[226:227], v[222:223]
	v_pk_fma_f32 v[244:245], v[244:245], v[228:229], v[224:225]
	v_cvt_pk_bf16_f32 v250, v242, v243
	v_cvt_pk_bf16_f32 v251, v244, v245
	global_store_dwordx4 v231, v[248:251], s[70:71] offset:3072
	s_nop 1
	s_add_u32 s26, s16, 8192
	s_addc_u32 s27, s17, 0
	s_add_u32 s24, s26, 0x1000
	s_addc_u32 s25, s27, 0
	global_load_dwordx4 v[66:69], v230, s[26:27] nt
	global_load_dwordx4 v[70:73], v230, s[26:27] offset:16 nt
	global_load_dwordx4 v[74:77], v230, s[26:27] offset:2048 nt
	global_load_dwordx4 v[78:81], v230, s[26:27] offset:2064 nt
	global_load_dwordx4 v[82:85], v230, s[24:25] nt
	global_load_dwordx4 v[86:89], v230, s[24:25] offset:16 nt
	global_load_dwordx4 v[90:93], v230, s[24:25] offset:2048 nt
	global_load_dwordx4 v[94:97], v230, s[24:25] offset:2064 nt
	s_waitcnt vmcnt(24)
	s_add_u32 s28, s18, 0
	s_lshr_b32 s29, s28, 6
	s_lshl_b32 s29, s29, 12
	s_add_u32 s29, s29, 0x80000
	s_add_u32 s30, s62, s29
	s_addc_u32 s31, s63, 0
	s_and_b32 s29, s28, 63
	s_add_u32 s29, s29, 16
	s_lshl_b32 s29, s29, 12
	s_add_u32 s29, s29, 0x80000
	s_add_u32 s36, s62, s29
	s_addc_u32 s37, s63, 0
	global_load_dwordx4 v[98:101], v230, s[30:31]
	global_load_dwordx4 v[102:105], v230, s[30:31] offset:16
	global_load_dwordx4 v[106:109], v230, s[30:31] offset:2048
	global_load_dwordx4 v[110:113], v230, s[30:31] offset:2064
	global_load_dwordx4 v[114:117], v230, s[36:37]
	global_load_dwordx4 v[118:121], v230, s[36:37] offset:16
	global_load_dwordx4 v[122:125], v230, s[36:37] offset:2048
	global_load_dwordx4 v[126:129], v230, s[36:37] offset:2064
	v_pk_mul_f32 v[232:233], v[2:3], v[2:3]
	v_pk_fma_f32 v[232:233], v[4:5], v[4:5], v[232:233]
	v_pk_fma_f32 v[232:233], v[6:7], v[6:7], v[232:233]
	v_pk_fma_f32 v[232:233], v[8:9], v[8:9], v[232:233]
	v_pk_fma_f32 v[232:233], v[10:11], v[10:11], v[232:233]
	v_pk_fma_f32 v[232:233], v[12:13], v[12:13], v[232:233]
	v_pk_fma_f32 v[232:233], v[14:15], v[14:15], v[232:233]
	v_pk_fma_f32 v[232:233], v[16:17], v[16:17], v[232:233]
	v_pk_fma_f32 v[232:233], v[18:19], v[18:19], v[232:233]
	v_pk_fma_f32 v[232:233], v[20:21], v[20:21], v[232:233]
	v_pk_fma_f32 v[232:233], v[22:23], v[22:23], v[232:233]
	v_pk_fma_f32 v[232:233], v[24:25], v[24:25], v[232:233]
	v_pk_fma_f32 v[232:233], v[26:27], v[26:27], v[232:233]
	v_pk_fma_f32 v[232:233], v[28:29], v[28:29], v[232:233]
	v_pk_fma_f32 v[232:233], v[30:31], v[30:31], v[232:233]
	v_pk_fma_f32 v[232:233], v[32:33], v[32:33], v[232:233]
	v_add_f32_e32 v232, v232, v233
	s_nop 1
	v_add_f32_dpp v232, v232, v232 quad_perm:[1,0,3,2] row_mask:0xf bank_mask:0xf
	s_nop 1
	v_add_f32_dpp v232, v232, v232 quad_perm:[2,3,0,1] row_mask:0xf bank_mask:0xf
	s_nop 1
	v_add_f32_dpp v232, v232, v232 row_half_mirror row_mask:0xf bank_mask:0xf
	s_nop 1
	v_add_f32_dpp v232, v232, v232 row_mirror row_mask:0xf bank_mask:0xf
	s_nop 1
	v_readlane_b32 s0, v232, 0
	v_readlane_b32 s1, v232, 16
	v_readlane_b32 s68, v232, 32
	v_readlane_b32 s69, v232, 48
	s_nop 3
	v_mov_b32_e32 v234, s0
	v_add_f32_e32 v234, s1, v234
	v_add_f32_e32 v234, s68, v234
	v_add_f32_e32 v234, s69, v234
	v_fmaak_f32 v234, v234, v246, 0x358637bd
	v_rsq_f32_e32 v234, v234
	s_nop 0
	v_mov_b32_e32 v235, v234
	s_add_u32 s70, s22, 16781312
	s_addc_u32 s71, s23, 0
	v_pk_mul_f32 v[238:239], v[2:3], v[234:235]
	v_pk_mul_f32 v[240:241], v[4:5], v[234:235]
	v_pk_mul_f32 v[238:239], v[130:131], v[238:239]
	v_pk_mul_f32 v[240:241], v[132:133], v[240:241]
	v_pk_fma_f32 v[238:239], v[238:239], v[162:163], v[194:195]
	v_pk_fma_f32 v[240:241], v[240:241], v[164:165], v[196:197]
	v_cvt_pk_bf16_f32 v248, v238, v239
	v_cvt_pk_bf16_f32 v249, v240, v241
	v_pk_mul_f32 v[242:243], v[6:7], v[234:235]
	v_pk_mul_f32 v[244:245], v[8:9], v[234:235]
	v_pk_mul_f32 v[242:243], v[134:135], v[242:243]
	v_pk_mul_f32 v[244:245], v[136:137], v[244:245]
	v_pk_fma_f32 v[242:243], v[242:243], v[166:167], v[198:199]
	v_pk_fma_f32 v[244:245], v[244:245], v[168:169], v[200:201]
	v_cvt_pk_bf16_f32 v250, v242, v243
	v_cvt_pk_bf16_f32 v251, v244, v245
	global_store_dwordx4 v231, v[248:251], s[70:71]
	s_nop 1
	v_pk_mul_f32 v[238:239], v[10:11], v[234:235]
	v_pk_mul_f32 v[240:241], v[12:13], v[234:235]
	v_pk_mul_f32 v[238:239], v[138:139], v[238:239]
	v_pk_mul_f32 v[240:241], v[140:141], v[240:241]
	v_pk_fma_f32 v[238:239], v[238:239], v[170:171], v[202:203]
	v_pk_fma_f32 v[240:241], v[240:241], v[172:173], v[204:205]
	v_cvt_pk_bf16_f32 v248, v238, v239
	v_cvt_pk_bf16_f32 v249, v240, v241
	v_pk_mul_f32 v[242:243], v[14:15], v[234:235]
	v_pk_mul_f32 v[244:245], v[16:17], v[234:235]
	v_pk_mul_f32 v[242:243], v[142:143], v[242:243]
	v_pk_mul_f32 v[244:245], v[144:145], v[244:245]
	v_pk_fma_f32 v[242:243], v[242:243], v[174:175], v[206:207]
	v_pk_fma_f32 v[244:245], v[244:245], v[176:177], v[208:209]
	v_cvt_pk_bf16_f32 v250, v242, v243
	v_cvt_pk_bf16_f32 v251, v244, v245
	global_store_dwordx4 v231, v[248:251], s[70:71] offset:1024
	s_nop 1
	v_pk_mul_f32 v[238:239], v[18:19], v[234:235]
	v_pk_mul_f32 v[240:241], v[20:21], v[234:235]
	v_pk_mul_f32 v[238:239], v[146:147], v[238:239]
	v_pk_mul_f32 v[240:241], v[148:149], v[240:241]
	v_pk_fma_f32 v[238:239], v[238:239], v[178:179], v[210:211]
	v_pk_fma_f32 v[240:241], v[240:241], v[180:181], v[212:213]
	v_cvt_pk_bf16_f32 v248, v238, v239
	v_cvt_pk_bf16_f32 v249, v240, v241
	v_pk_mul_f32 v[242:243], v[22:23], v[234:235]
	v_pk_mul_f32 v[244:245], v[24:25], v[234:235]
	v_pk_mul_f32 v[242:243], v[150:151], v[242:243]
	v_pk_mul_f32 v[244:245], v[152:153], v[244:245]
	v_pk_fma_f32 v[242:243], v[242:243], v[182:183], v[214:215]
	v_pk_fma_f32 v[244:245], v[244:245], v[184:185], v[216:217]
	v_cvt_pk_bf16_f32 v250, v242, v243
	v_cvt_pk_bf16_f32 v251, v244, v245
	global_store_dwordx4 v231, v[248:251], s[70:71] offset:2048
	s_nop 1
	v_pk_mul_f32 v[238:239], v[26:27], v[234:235]
	v_pk_mul_f32 v[240:241], v[28:29], v[234:235]
	v_pk_mul_f32 v[238:239], v[154:155], v[238:239]
	v_pk_mul_f32 v[240:241], v[156:157], v[240:241]
	v_pk_fma_f32 v[238:239], v[238:239], v[186:187], v[218:219]
	v_pk_fma_f32 v[240:241], v[240:241], v[188:189], v[220:221]
	v_cvt_pk_bf16_f32 v248, v238, v239
	v_cvt_pk_bf16_f32 v249, v240, v241
	v_pk_mul_f32 v[242:243], v[30:31], v[234:235]
	v_pk_mul_f32 v[244:245], v[32:33], v[234:235]
	v_pk_mul_f32 v[242:243], v[158:159], v[242:243]
	v_pk_mul_f32 v[244:245], v[160:161], v[244:245]
	v_pk_fma_f32 v[242:243], v[242:243], v[226:227], v[222:223]
	v_pk_fma_f32 v[244:245], v[244:245], v[228:229], v[224:225]
	v_cvt_pk_bf16_f32 v250, v242, v243
	v_cvt_pk_bf16_f32 v251, v244, v245
	global_store_dwordx4 v231, v[248:251], s[70:71] offset:3072
	s_nop 1
	s_add_u32 s38, s19, 1
	s_mul_i32 s38, s38, 0xc000
	s_add_u32 s38, s62, s38
	s_addc_u32 s39, s63, 0
	s_add_u32 s40, s38, 0x2000
	s_addc_u32 s41, s39, 0
	s_add_u32 s64, s38, 0x1000
	s_addc_u32 s65, s39, 0
	s_add_u32 s66, s40, 0x1000
	s_addc_u32 s67, s41, 0
	global_load_dwordx4 v[194:197], v230, s[38:39]
	global_load_dwordx4 v[162:165], v230, s[40:41]
	global_load_dwordx4 v[198:201], v230, s[38:39] offset:16
	global_load_dwordx4 v[166:169], v230, s[40:41] offset:16
	global_load_dwordx4 v[202:205], v230, s[38:39] offset:2048
	global_load_dwordx4 v[170:173], v230, s[40:41] offset:2048
	global_load_dwordx4 v[206:209], v230, s[38:39] offset:2064
	global_load_dwordx4 v[174:177], v230, s[40:41] offset:2064
	global_load_dwordx4 v[210:213], v230, s[64:65]
	global_load_dwordx4 v[178:181], v230, s[66:67]
	global_load_dwordx4 v[214:217], v230, s[64:65] offset:16
	global_load_dwordx4 v[182:185], v230, s[66:67] offset:16
	global_load_dwordx4 v[218:221], v230, s[64:65] offset:2048
	global_load_dwordx4 v[186:189], v230, s[66:67] offset:2048
	global_load_dwordx4 v[222:225], v230, s[64:65] offset:2064
	global_load_dwordx4 v[226:229], v230, s[66:67] offset:2064
	s_add_u32 s26, s16, 33554432
	s_addc_u32 s27, s17, 0
	s_add_u32 s24, s26, 0x1000
	s_addc_u32 s25, s27, 0
	global_load_dwordx4 v[2:5], v230, s[26:27] nt
	global_load_dwordx4 v[6:9], v230, s[26:27] offset:16 nt
	global_load_dwordx4 v[10:13], v230, s[26:27] offset:2048 nt
	global_load_dwordx4 v[14:17], v230, s[26:27] offset:2064 nt
	global_load_dwordx4 v[18:21], v230, s[24:25] nt
	global_load_dwordx4 v[22:25], v230, s[24:25] offset:16 nt
	global_load_dwordx4 v[26:29], v230, s[24:25] offset:2048 nt
	global_load_dwordx4 v[30:33], v230, s[24:25] offset:2064 nt
	s_waitcnt vmcnt(28)
	v_pk_add_f32 v[34:35], v[34:35], v[98:99]
	v_pk_add_f32 v[36:37], v[36:37], v[100:101]
	v_pk_add_f32 v[38:39], v[38:39], v[102:103]
	v_pk_add_f32 v[40:41], v[40:41], v[104:105]
	v_pk_add_f32 v[42:43], v[42:43], v[106:107]
	v_pk_add_f32 v[44:45], v[44:45], v[108:109]
	v_pk_add_f32 v[46:47], v[46:47], v[110:111]
	v_pk_add_f32 v[48:49], v[48:49], v[112:113]
	v_pk_add_f32 v[50:51], v[50:51], v[114:115]
	v_pk_add_f32 v[52:53], v[52:53], v[116:117]
	v_pk_add_f32 v[54:55], v[54:55], v[118:119]
	v_pk_add_f32 v[56:57], v[56:57], v[120:121]
	v_pk_add_f32 v[58:59], v[58:59], v[122:123]
	v_pk_add_f32 v[60:61], v[60:61], v[124:125]
	v_pk_add_f32 v[62:63], v[62:63], v[126:127]
	v_pk_add_f32 v[64:65], v[64:65], v[128:129]
	s_add_u32 s28, s18, 1
	s_lshr_b32 s29, s28, 6
	s_lshl_b32 s29, s29, 12
	s_add_u32 s29, s29, 0x80000
	s_add_u32 s30, s62, s29
	s_addc_u32 s31, s63, 0
	s_and_b32 s29, s28, 63
	s_add_u32 s29, s29, 16
	s_lshl_b32 s29, s29, 12
	s_add_u32 s29, s29, 0x80000
	s_add_u32 s36, s62, s29
	s_addc_u32 s37, s63, 0
	global_load_dwordx4 v[98:101], v230, s[30:31]
	global_load_dwordx4 v[102:105], v230, s[30:31] offset:16
	global_load_dwordx4 v[106:109], v230, s[30:31] offset:2048
	global_load_dwordx4 v[110:113], v230, s[30:31] offset:2064
	global_load_dwordx4 v[114:117], v230, s[36:37]
	global_load_dwordx4 v[118:121], v230, s[36:37] offset:16
	global_load_dwordx4 v[122:125], v230, s[36:37] offset:2048
	global_load_dwordx4 v[126:129], v230, s[36:37] offset:2064
	v_pk_mul_f32 v[232:233], v[34:35], v[34:35]
	v_pk_fma_f32 v[232:233], v[36:37], v[36:37], v[232:233]
	v_pk_fma_f32 v[232:233], v[38:39], v[38:39], v[232:233]
	v_pk_fma_f32 v[232:233], v[40:41], v[40:41], v[232:233]
	v_pk_fma_f32 v[232:233], v[42:43], v[42:43], v[232:233]
	v_pk_fma_f32 v[232:233], v[44:45], v[44:45], v[232:233]
	v_pk_fma_f32 v[232:233], v[46:47], v[46:47], v[232:233]
	v_pk_fma_f32 v[232:233], v[48:49], v[48:49], v[232:233]
	v_pk_fma_f32 v[232:233], v[50:51], v[50:51], v[232:233]
	v_pk_fma_f32 v[232:233], v[52:53], v[52:53], v[232:233]
	v_pk_fma_f32 v[232:233], v[54:55], v[54:55], v[232:233]
	v_pk_fma_f32 v[232:233], v[56:57], v[56:57], v[232:233]
	v_pk_fma_f32 v[232:233], v[58:59], v[58:59], v[232:233]
	v_pk_fma_f32 v[232:233], v[60:61], v[60:61], v[232:233]
	v_pk_fma_f32 v[232:233], v[62:63], v[62:63], v[232:233]
	v_pk_fma_f32 v[232:233], v[64:65], v[64:65], v[232:233]
	v_add_f32_e32 v232, v232, v233
	s_nop 1
	v_add_f32_dpp v232, v232, v232 quad_perm:[1,0,3,2] row_mask:0xf bank_mask:0xf
	s_nop 1
	v_add_f32_dpp v232, v232, v232 quad_perm:[2,3,0,1] row_mask:0xf bank_mask:0xf
	s_nop 1
	v_add_f32_dpp v232, v232, v232 row_half_mirror row_mask:0xf bank_mask:0xf
	s_nop 1
	v_add_f32_dpp v232, v232, v232 row_mirror row_mask:0xf bank_mask:0xf
	s_nop 1
	v_readlane_b32 s0, v232, 0
	v_readlane_b32 s1, v232, 16
	v_readlane_b32 s68, v232, 32
	v_readlane_b32 s69, v232, 48
	s_nop 3
	v_mov_b32_e32 v234, s0
	v_add_f32_e32 v234, s1, v234
	v_add_f32_e32 v234, s68, v234
	v_add_f32_e32 v234, s69, v234
	v_fmaak_f32 v234, v234, v246, 0x358637bd
	v_rsq_f32_e32 v234, v234
	s_nop 0
	v_mov_b32_e32 v235, v234
	s_waitcnt vmcnt(16)
	v_pk_add_f32 v[162:163], v[162:163], 1.0 op_sel_hi:[1,0]
	v_pk_add_f32 v[164:165], v[164:165], 1.0 op_sel_hi:[1,0]
	v_pk_add_f32 v[166:167], v[166:167], 1.0 op_sel_hi:[1,0]
	v_pk_add_f32 v[168:169], v[168:169], 1.0 op_sel_hi:[1,0]
	v_pk_add_f32 v[170:171], v[170:171], 1.0 op_sel_hi:[1,0]
	v_pk_add_f32 v[172:173], v[172:173], 1.0 op_sel_hi:[1,0]
	v_pk_add_f32 v[174:175], v[174:175], 1.0 op_sel_hi:[1,0]
	v_pk_add_f32 v[176:177], v[176:177], 1.0 op_sel_hi:[1,0]
	v_pk_add_f32 v[178:179], v[178:179], 1.0 op_sel_hi:[1,0]
	v_pk_add_f32 v[180:181], v[180:181], 1.0 op_sel_hi:[1,0]
	v_pk_add_f32 v[182:183], v[182:183], 1.0 op_sel_hi:[1,0]
	v_pk_add_f32 v[184:185], v[184:185], 1.0 op_sel_hi:[1,0]
	v_pk_add_f32 v[186:187], v[186:187], 1.0 op_sel_hi:[1,0]
	v_pk_add_f32 v[188:189], v[188:189], 1.0 op_sel_hi:[1,0]
	v_pk_add_f32 v[226:227], v[226:227], 1.0 op_sel_hi:[1,0]
	v_pk_add_f32 v[228:229], v[228:229], 1.0 op_sel_hi:[1,0]
	s_add_u32 s70, s22, 33554432
	s_addc_u32 s71, s23, 0
	v_pk_mul_f32 v[238:239], v[34:35], v[234:235]
	v_pk_mul_f32 v[240:241], v[36:37], v[234:235]
	v_pk_mul_f32 v[238:239], v[130:131], v[238:239]
	v_pk_mul_f32 v[240:241], v[132:133], v[240:241]
	v_pk_fma_f32 v[238:239], v[238:239], v[162:163], v[194:195]
	v_pk_fma_f32 v[240:241], v[240:241], v[164:165], v[196:197]
	v_cvt_pk_bf16_f32 v248, v238, v239
	v_cvt_pk_bf16_f32 v249, v240, v241
	v_pk_mul_f32 v[242:243], v[38:39], v[234:235]
	v_pk_mul_f32 v[244:245], v[40:41], v[234:235]
	v_pk_mul_f32 v[242:243], v[134:135], v[242:243]
	v_pk_mul_f32 v[244:245], v[136:137], v[244:245]
	v_pk_fma_f32 v[242:243], v[242:243], v[166:167], v[198:199]
	v_pk_fma_f32 v[244:245], v[244:245], v[168:169], v[200:201]
	v_cvt_pk_bf16_f32 v250, v242, v243
	v_cvt_pk_bf16_f32 v251, v244, v245
	global_store_dwordx4 v231, v[248:251], s[70:71]
	s_nop 1
	v_pk_mul_f32 v[238:239], v[42:43], v[234:235]
	v_pk_mul_f32 v[240:241], v[44:45], v[234:235]
	v_pk_mul_f32 v[238:239], v[138:139], v[238:239]
	v_pk_mul_f32 v[240:241], v[140:141], v[240:241]
	v_pk_fma_f32 v[238:239], v[238:239], v[170:171], v[202:203]
	v_pk_fma_f32 v[240:241], v[240:241], v[172:173], v[204:205]
	v_cvt_pk_bf16_f32 v248, v238, v239
	v_cvt_pk_bf16_f32 v249, v240, v241
	v_pk_mul_f32 v[242:243], v[46:47], v[234:235]
	v_pk_mul_f32 v[244:245], v[48:49], v[234:235]
	v_pk_mul_f32 v[242:243], v[142:143], v[242:243]
	v_pk_mul_f32 v[244:245], v[144:145], v[244:245]
	v_pk_fma_f32 v[242:243], v[242:243], v[174:175], v[206:207]
	v_pk_fma_f32 v[244:245], v[244:245], v[176:177], v[208:209]
	v_cvt_pk_bf16_f32 v250, v242, v243
	v_cvt_pk_bf16_f32 v251, v244, v245
	global_store_dwordx4 v231, v[248:251], s[70:71] offset:1024
	s_nop 1
	v_pk_mul_f32 v[238:239], v[50:51], v[234:235]
	v_pk_mul_f32 v[240:241], v[52:53], v[234:235]
	v_pk_mul_f32 v[238:239], v[146:147], v[238:239]
	v_pk_mul_f32 v[240:241], v[148:149], v[240:241]
	v_pk_fma_f32 v[238:239], v[238:239], v[178:179], v[210:211]
	v_pk_fma_f32 v[240:241], v[240:241], v[180:181], v[212:213]
	v_cvt_pk_bf16_f32 v248, v238, v239
	v_cvt_pk_bf16_f32 v249, v240, v241
	v_pk_mul_f32 v[242:243], v[54:55], v[234:235]
	v_pk_mul_f32 v[244:245], v[56:57], v[234:235]
	v_pk_mul_f32 v[242:243], v[150:151], v[242:243]
	v_pk_mul_f32 v[244:245], v[152:153], v[244:245]
	v_pk_fma_f32 v[242:243], v[242:243], v[182:183], v[214:215]
	v_pk_fma_f32 v[244:245], v[244:245], v[184:185], v[216:217]
	v_cvt_pk_bf16_f32 v250, v242, v243
	v_cvt_pk_bf16_f32 v251, v244, v245
	global_store_dwordx4 v231, v[248:251], s[70:71] offset:2048
	s_nop 1
	v_pk_mul_f32 v[238:239], v[58:59], v[234:235]
	v_pk_mul_f32 v[240:241], v[60:61], v[234:235]
	v_pk_mul_f32 v[238:239], v[154:155], v[238:239]
	v_pk_mul_f32 v[240:241], v[156:157], v[240:241]
	v_pk_fma_f32 v[238:239], v[238:239], v[186:187], v[218:219]
	v_pk_fma_f32 v[240:241], v[240:241], v[188:189], v[220:221]
	v_cvt_pk_bf16_f32 v248, v238, v239
	v_cvt_pk_bf16_f32 v249, v240, v241
	v_pk_mul_f32 v[242:243], v[62:63], v[234:235]
	v_pk_mul_f32 v[244:245], v[64:65], v[234:235]
	v_pk_mul_f32 v[242:243], v[158:159], v[242:243]
	v_pk_mul_f32 v[244:245], v[160:161], v[244:245]
	v_pk_fma_f32 v[242:243], v[242:243], v[226:227], v[222:223]
	v_pk_fma_f32 v[244:245], v[244:245], v[228:229], v[224:225]
	v_cvt_pk_bf16_f32 v250, v242, v243
	v_cvt_pk_bf16_f32 v251, v244, v245
	global_store_dwordx4 v231, v[248:251], s[70:71] offset:3072
	s_nop 1
	s_add_u32 s26, s16, 33562624
	s_addc_u32 s27, s17, 0
	s_add_u32 s24, s26, 0x1000
	s_addc_u32 s25, s27, 0
	global_load_dwordx4 v[34:37], v230, s[26:27] nt
	global_load_dwordx4 v[38:41], v230, s[26:27] offset:16 nt
	global_load_dwordx4 v[42:45], v230, s[26:27] offset:2048 nt
	global_load_dwordx4 v[46:49], v230, s[26:27] offset:2064 nt
	global_load_dwordx4 v[50:53], v230, s[24:25] nt
	global_load_dwordx4 v[54:57], v230, s[24:25] offset:16 nt
	global_load_dwordx4 v[58:61], v230, s[24:25] offset:2048 nt
	global_load_dwordx4 v[62:65], v230, s[24:25] offset:2064 nt
	s_waitcnt vmcnt(12)
	v_pk_add_f32 v[66:67], v[66:67], v[98:99]
	v_pk_add_f32 v[68:69], v[68:69], v[100:101]
	v_pk_add_f32 v[70:71], v[70:71], v[102:103]
	v_pk_add_f32 v[72:73], v[72:73], v[104:105]
	v_pk_add_f32 v[74:75], v[74:75], v[106:107]
	v_pk_add_f32 v[76:77], v[76:77], v[108:109]
	v_pk_add_f32 v[78:79], v[78:79], v[110:111]
	v_pk_add_f32 v[80:81], v[80:81], v[112:113]
	v_pk_add_f32 v[82:83], v[82:83], v[114:115]
	v_pk_add_f32 v[84:85], v[84:85], v[116:117]
	v_pk_add_f32 v[86:87], v[86:87], v[118:119]
	v_pk_add_f32 v[88:89], v[88:89], v[120:121]
	v_pk_add_f32 v[90:91], v[90:91], v[122:123]
	v_pk_add_f32 v[92:93], v[92:93], v[124:125]
	v_pk_add_f32 v[94:95], v[94:95], v[126:127]
	v_pk_add_f32 v[96:97], v[96:97], v[128:129]
	s_add_u32 s28, s18, 0
	s_lshr_b32 s29, s28, 6
	s_lshl_b32 s29, s29, 12
	s_add_u32 s29, s29, 0x80000
	s_add_u32 s30, s62, s29
	s_addc_u32 s31, s63, 0
	s_and_b32 s29, s28, 63
	s_add_u32 s29, s29, 16
	s_lshl_b32 s29, s29, 12
	s_add_u32 s29, s29, 0x80000
	s_add_u32 s36, s62, s29
	s_addc_u32 s37, s63, 0
	global_load_dwordx4 v[98:101], v230, s[30:31]
	global_load_dwordx4 v[102:105], v230, s[30:31] offset:16
	global_load_dwordx4 v[106:109], v230, s[30:31] offset:2048
	global_load_dwordx4 v[110:113], v230, s[30:31] offset:2064
	global_load_dwordx4 v[114:117], v230, s[36:37]
	global_load_dwordx4 v[118:121], v230, s[36:37] offset:16
	global_load_dwordx4 v[122:125], v230, s[36:37] offset:2048
	global_load_dwordx4 v[126:129], v230, s[36:37] offset:2064
	v_pk_mul_f32 v[232:233], v[66:67], v[66:67]
	v_pk_fma_f32 v[232:233], v[68:69], v[68:69], v[232:233]
	v_pk_fma_f32 v[232:233], v[70:71], v[70:71], v[232:233]
	v_pk_fma_f32 v[232:233], v[72:73], v[72:73], v[232:233]
	v_pk_fma_f32 v[232:233], v[74:75], v[74:75], v[232:233]
	v_pk_fma_f32 v[232:233], v[76:77], v[76:77], v[232:233]
	v_pk_fma_f32 v[232:233], v[78:79], v[78:79], v[232:233]
	v_pk_fma_f32 v[232:233], v[80:81], v[80:81], v[232:233]
	v_pk_fma_f32 v[232:233], v[82:83], v[82:83], v[232:233]
	v_pk_fma_f32 v[232:233], v[84:85], v[84:85], v[232:233]
	v_pk_fma_f32 v[232:233], v[86:87], v[86:87], v[232:233]
	v_pk_fma_f32 v[232:233], v[88:89], v[88:89], v[232:233]
	v_pk_fma_f32 v[232:233], v[90:91], v[90:91], v[232:233]
	v_pk_fma_f32 v[232:233], v[92:93], v[92:93], v[232:233]
	v_pk_fma_f32 v[232:233], v[94:95], v[94:95], v[232:233]
	v_pk_fma_f32 v[232:233], v[96:97], v[96:97], v[232:233]
	v_add_f32_e32 v232, v232, v233
	s_nop 1
	v_add_f32_dpp v232, v232, v232 quad_perm:[1,0,3,2] row_mask:0xf bank_mask:0xf
	s_nop 1
	v_add_f32_dpp v232, v232, v232 quad_perm:[2,3,0,1] row_mask:0xf bank_mask:0xf
	s_nop 1
	v_add_f32_dpp v232, v232, v232 row_half_mirror row_mask:0xf bank_mask:0xf
	s_nop 1
	v_add_f32_dpp v232, v232, v232 row_mirror row_mask:0xf bank_mask:0xf
	s_nop 1
	v_readlane_b32 s0, v232, 0
	v_readlane_b32 s1, v232, 16
	v_readlane_b32 s68, v232, 32
	v_readlane_b32 s69, v232, 48
	s_nop 3
	v_mov_b32_e32 v234, s0
	v_add_f32_e32 v234, s1, v234
	v_add_f32_e32 v234, s68, v234
	v_add_f32_e32 v234, s69, v234
	v_fmaak_f32 v234, v234, v246, 0x358637bd
	v_rsq_f32_e32 v234, v234
	s_nop 0
	v_mov_b32_e32 v235, v234
	s_add_u32 s70, s22, 33558528
	s_addc_u32 s71, s23, 0
	v_pk_mul_f32 v[238:239], v[66:67], v[234:235]
	v_pk_mul_f32 v[240:241], v[68:69], v[234:235]
	v_pk_mul_f32 v[238:239], v[130:131], v[238:239]
	v_pk_mul_f32 v[240:241], v[132:133], v[240:241]
	v_pk_fma_f32 v[238:239], v[238:239], v[162:163], v[194:195]
	v_pk_fma_f32 v[240:241], v[240:241], v[164:165], v[196:197]
	v_cvt_pk_bf16_f32 v248, v238, v239
	v_cvt_pk_bf16_f32 v249, v240, v241
	v_pk_mul_f32 v[242:243], v[70:71], v[234:235]
	v_pk_mul_f32 v[244:245], v[72:73], v[234:235]
	v_pk_mul_f32 v[242:243], v[134:135], v[242:243]
	v_pk_mul_f32 v[244:245], v[136:137], v[244:245]
	v_pk_fma_f32 v[242:243], v[242:243], v[166:167], v[198:199]
	v_pk_fma_f32 v[244:245], v[244:245], v[168:169], v[200:201]
	v_cvt_pk_bf16_f32 v250, v242, v243
	v_cvt_pk_bf16_f32 v251, v244, v245
	global_store_dwordx4 v231, v[248:251], s[70:71]
	s_nop 1
	v_pk_mul_f32 v[238:239], v[74:75], v[234:235]
	v_pk_mul_f32 v[240:241], v[76:77], v[234:235]
	v_pk_mul_f32 v[238:239], v[138:139], v[238:239]
	v_pk_mul_f32 v[240:241], v[140:141], v[240:241]
	v_pk_fma_f32 v[238:239], v[238:239], v[170:171], v[202:203]
	v_pk_fma_f32 v[240:241], v[240:241], v[172:173], v[204:205]
	v_cvt_pk_bf16_f32 v248, v238, v239
	v_cvt_pk_bf16_f32 v249, v240, v241
	v_pk_mul_f32 v[242:243], v[78:79], v[234:235]
	v_pk_mul_f32 v[244:245], v[80:81], v[234:235]
	v_pk_mul_f32 v[242:243], v[142:143], v[242:243]
	v_pk_mul_f32 v[244:245], v[144:145], v[244:245]
	v_pk_fma_f32 v[242:243], v[242:243], v[174:175], v[206:207]
	v_pk_fma_f32 v[244:245], v[244:245], v[176:177], v[208:209]
	v_cvt_pk_bf16_f32 v250, v242, v243
	v_cvt_pk_bf16_f32 v251, v244, v245
	global_store_dwordx4 v231, v[248:251], s[70:71] offset:1024
	s_nop 1
	v_pk_mul_f32 v[238:239], v[82:83], v[234:235]
	v_pk_mul_f32 v[240:241], v[84:85], v[234:235]
	v_pk_mul_f32 v[238:239], v[146:147], v[238:239]
	v_pk_mul_f32 v[240:241], v[148:149], v[240:241]
	v_pk_fma_f32 v[238:239], v[238:239], v[178:179], v[210:211]
	v_pk_fma_f32 v[240:241], v[240:241], v[180:181], v[212:213]
	v_cvt_pk_bf16_f32 v248, v238, v239
	v_cvt_pk_bf16_f32 v249, v240, v241
	v_pk_mul_f32 v[242:243], v[86:87], v[234:235]
	v_pk_mul_f32 v[244:245], v[88:89], v[234:235]
	v_pk_mul_f32 v[242:243], v[150:151], v[242:243]
	v_pk_mul_f32 v[244:245], v[152:153], v[244:245]
	v_pk_fma_f32 v[242:243], v[242:243], v[182:183], v[214:215]
	v_pk_fma_f32 v[244:245], v[244:245], v[184:185], v[216:217]
	v_cvt_pk_bf16_f32 v250, v242, v243
	v_cvt_pk_bf16_f32 v251, v244, v245
	global_store_dwordx4 v231, v[248:251], s[70:71] offset:2048
	s_nop 1
	v_pk_mul_f32 v[238:239], v[90:91], v[234:235]
	v_pk_mul_f32 v[240:241], v[92:93], v[234:235]
	v_pk_mul_f32 v[238:239], v[154:155], v[238:239]
	v_pk_mul_f32 v[240:241], v[156:157], v[240:241]
	v_pk_fma_f32 v[238:239], v[238:239], v[186:187], v[218:219]
	v_pk_fma_f32 v[240:241], v[240:241], v[188:189], v[220:221]
	v_cvt_pk_bf16_f32 v248, v238, v239
	v_cvt_pk_bf16_f32 v249, v240, v241
	v_pk_mul_f32 v[242:243], v[94:95], v[234:235]
	v_pk_mul_f32 v[244:245], v[96:97], v[234:235]
	v_pk_mul_f32 v[242:243], v[158:159], v[242:243]
	v_pk_mul_f32 v[244:245], v[160:161], v[244:245]
	v_pk_fma_f32 v[242:243], v[242:243], v[226:227], v[222:223]
	v_pk_fma_f32 v[244:245], v[244:245], v[228:229], v[224:225]
	v_cvt_pk_bf16_f32 v250, v242, v243
	v_cvt_pk_bf16_f32 v251, v244, v245
	global_store_dwordx4 v231, v[248:251], s[70:71] offset:3072
	s_nop 1
	s_add_u32 s38, s19, 5
	s_mul_i32 s38, s38, 0xc000
	s_add_u32 s38, s62, s38
	s_addc_u32 s39, s63, 0
	s_add_u32 s40, s38, 0x2000
	s_addc_u32 s41, s39, 0
	s_add_u32 s64, s38, 0x1000
	s_addc_u32 s65, s39, 0
	s_add_u32 s66, s40, 0x1000
	s_addc_u32 s67, s41, 0
	global_load_dwordx4 v[194:197], v230, s[38:39]
	global_load_dwordx4 v[162:165], v230, s[40:41]
	global_load_dwordx4 v[198:201], v230, s[38:39] offset:16
	global_load_dwordx4 v[166:169], v230, s[40:41] offset:16
	global_load_dwordx4 v[202:205], v230, s[38:39] offset:2048
	global_load_dwordx4 v[170:173], v230, s[40:41] offset:2048
	global_load_dwordx4 v[206:209], v230, s[38:39] offset:2064
	global_load_dwordx4 v[174:177], v230, s[40:41] offset:2064
	global_load_dwordx4 v[210:213], v230, s[64:65]
	global_load_dwordx4 v[178:181], v230, s[66:67]
	global_load_dwordx4 v[214:217], v230, s[64:65] offset:16
	global_load_dwordx4 v[182:185], v230, s[66:67] offset:16
	global_load_dwordx4 v[218:221], v230, s[64:65] offset:2048
	global_load_dwordx4 v[186:189], v230, s[66:67] offset:2048
	global_load_dwordx4 v[222:225], v230, s[64:65] offset:2064
	global_load_dwordx4 v[226:229], v230, s[66:67] offset:2064
	s_waitcnt vmcnt(20)
	v_pk_add_f32 v[2:3], v[2:3], v[98:99]
	v_pk_add_f32 v[4:5], v[4:5], v[100:101]
	v_pk_add_f32 v[6:7], v[6:7], v[102:103]
	v_pk_add_f32 v[8:9], v[8:9], v[104:105]
	v_pk_add_f32 v[10:11], v[10:11], v[106:107]
	v_pk_add_f32 v[12:13], v[12:13], v[108:109]
	v_pk_add_f32 v[14:15], v[14:15], v[110:111]
	v_pk_add_f32 v[16:17], v[16:17], v[112:113]
	v_pk_add_f32 v[18:19], v[18:19], v[114:115]
	v_pk_add_f32 v[20:21], v[20:21], v[116:117]
	v_pk_add_f32 v[22:23], v[22:23], v[118:119]
	v_pk_add_f32 v[24:25], v[24:25], v[120:121]
	v_pk_add_f32 v[26:27], v[26:27], v[122:123]
	v_pk_add_f32 v[28:29], v[28:29], v[124:125]
	v_pk_add_f32 v[30:31], v[30:31], v[126:127]
	v_pk_add_f32 v[32:33], v[32:33], v[128:129]
	s_add_u32 s28, s18, 1
	s_lshr_b32 s29, s28, 6
	s_lshl_b32 s29, s29, 12
	s_add_u32 s29, s29, 0x80000
	s_add_u32 s30, s62, s29
	s_addc_u32 s31, s63, 0
	s_and_b32 s29, s28, 63
	s_add_u32 s29, s29, 16
	s_lshl_b32 s29, s29, 12
	s_add_u32 s29, s29, 0x80000
	s_add_u32 s36, s62, s29
	s_addc_u32 s37, s63, 0
	global_load_dwordx4 v[98:101], v230, s[30:31]
	global_load_dwordx4 v[102:105], v230, s[30:31] offset:16
	global_load_dwordx4 v[106:109], v230, s[30:31] offset:2048
	global_load_dwordx4 v[110:113], v230, s[30:31] offset:2064
	global_load_dwordx4 v[114:117], v230, s[36:37]
	global_load_dwordx4 v[118:121], v230, s[36:37] offset:16
	global_load_dwordx4 v[122:125], v230, s[36:37] offset:2048
	global_load_dwordx4 v[126:129], v230, s[36:37] offset:2064
	v_pk_mul_f32 v[232:233], v[2:3], v[2:3]
	v_pk_fma_f32 v[232:233], v[4:5], v[4:5], v[232:233]
	v_pk_fma_f32 v[232:233], v[6:7], v[6:7], v[232:233]
	v_pk_fma_f32 v[232:233], v[8:9], v[8:9], v[232:233]
	v_pk_fma_f32 v[232:233], v[10:11], v[10:11], v[232:233]
	v_pk_fma_f32 v[232:233], v[12:13], v[12:13], v[232:233]
	v_pk_fma_f32 v[232:233], v[14:15], v[14:15], v[232:233]
	v_pk_fma_f32 v[232:233], v[16:17], v[16:17], v[232:233]
	v_pk_fma_f32 v[232:233], v[18:19], v[18:19], v[232:233]
	v_pk_fma_f32 v[232:233], v[20:21], v[20:21], v[232:233]
	v_pk_fma_f32 v[232:233], v[22:23], v[22:23], v[232:233]
	v_pk_fma_f32 v[232:233], v[24:25], v[24:25], v[232:233]
	v_pk_fma_f32 v[232:233], v[26:27], v[26:27], v[232:233]
	v_pk_fma_f32 v[232:233], v[28:29], v[28:29], v[232:233]
	v_pk_fma_f32 v[232:233], v[30:31], v[30:31], v[232:233]
	v_pk_fma_f32 v[232:233], v[32:33], v[32:33], v[232:233]
	v_add_f32_e32 v232, v232, v233
	s_nop 1
	v_add_f32_dpp v232, v232, v232 quad_perm:[1,0,3,2] row_mask:0xf bank_mask:0xf
	s_nop 1
	v_add_f32_dpp v232, v232, v232 quad_perm:[2,3,0,1] row_mask:0xf bank_mask:0xf
	s_nop 1
	v_add_f32_dpp v232, v232, v232 row_half_mirror row_mask:0xf bank_mask:0xf
	s_nop 1
	v_add_f32_dpp v232, v232, v232 row_mirror row_mask:0xf bank_mask:0xf
	s_nop 1
	v_readlane_b32 s0, v232, 0
	v_readlane_b32 s1, v232, 16
	v_readlane_b32 s68, v232, 32
	v_readlane_b32 s69, v232, 48
	s_nop 3
	v_mov_b32_e32 v234, s0
	v_add_f32_e32 v234, s1, v234
	v_add_f32_e32 v234, s68, v234
	v_add_f32_e32 v234, s69, v234
	v_fmaak_f32 v234, v234, v246, 0x358637bd
	v_rsq_f32_e32 v234, v234
	s_nop 0
	v_mov_b32_e32 v235, v234
	s_waitcnt vmcnt(8)
	v_pk_add_f32 v[162:163], v[162:163], 1.0 op_sel_hi:[1,0]
	v_pk_add_f32 v[164:165], v[164:165], 1.0 op_sel_hi:[1,0]
	v_pk_add_f32 v[166:167], v[166:167], 1.0 op_sel_hi:[1,0]
	v_pk_add_f32 v[168:169], v[168:169], 1.0 op_sel_hi:[1,0]
	v_pk_add_f32 v[170:171], v[170:171], 1.0 op_sel_hi:[1,0]
	v_pk_add_f32 v[172:173], v[172:173], 1.0 op_sel_hi:[1,0]
	v_pk_add_f32 v[174:175], v[174:175], 1.0 op_sel_hi:[1,0]
	v_pk_add_f32 v[176:177], v[176:177], 1.0 op_sel_hi:[1,0]
	v_pk_add_f32 v[178:179], v[178:179], 1.0 op_sel_hi:[1,0]
	v_pk_add_f32 v[180:181], v[180:181], 1.0 op_sel_hi:[1,0]
	v_pk_add_f32 v[182:183], v[182:183], 1.0 op_sel_hi:[1,0]
	v_pk_add_f32 v[184:185], v[184:185], 1.0 op_sel_hi:[1,0]
	v_pk_add_f32 v[186:187], v[186:187], 1.0 op_sel_hi:[1,0]
	v_pk_add_f32 v[188:189], v[188:189], 1.0 op_sel_hi:[1,0]
	v_pk_add_f32 v[226:227], v[226:227], 1.0 op_sel_hi:[1,0]
	v_pk_add_f32 v[228:229], v[228:229], 1.0 op_sel_hi:[1,0]
	s_add_u32 s70, s22, 50331648
	s_addc_u32 s71, s23, 0
	v_pk_mul_f32 v[238:239], v[2:3], v[234:235]
	v_pk_mul_f32 v[240:241], v[4:5], v[234:235]
	v_pk_mul_f32 v[238:239], v[130:131], v[238:239]
	v_pk_mul_f32 v[240:241], v[132:133], v[240:241]
	v_pk_fma_f32 v[238:239], v[238:239], v[162:163], v[194:195]
	v_pk_fma_f32 v[240:241], v[240:241], v[164:165], v[196:197]
	v_cvt_pk_bf16_f32 v248, v238, v239
	v_cvt_pk_bf16_f32 v249, v240, v241
	v_pk_mul_f32 v[242:243], v[6:7], v[234:235]
	v_pk_mul_f32 v[244:245], v[8:9], v[234:235]
	v_pk_mul_f32 v[242:243], v[134:135], v[242:243]
	v_pk_mul_f32 v[244:245], v[136:137], v[244:245]
	v_pk_fma_f32 v[242:243], v[242:243], v[166:167], v[198:199]
	v_pk_fma_f32 v[244:245], v[244:245], v[168:169], v[200:201]
	v_cvt_pk_bf16_f32 v250, v242, v243
	v_cvt_pk_bf16_f32 v251, v244, v245
	global_store_dwordx4 v231, v[248:251], s[70:71]
	s_nop 1
	v_pk_mul_f32 v[238:239], v[10:11], v[234:235]
	v_pk_mul_f32 v[240:241], v[12:13], v[234:235]
	v_pk_mul_f32 v[238:239], v[138:139], v[238:239]
	v_pk_mul_f32 v[240:241], v[140:141], v[240:241]
	v_pk_fma_f32 v[238:239], v[238:239], v[170:171], v[202:203]
	v_pk_fma_f32 v[240:241], v[240:241], v[172:173], v[204:205]
	v_cvt_pk_bf16_f32 v248, v238, v239
	v_cvt_pk_bf16_f32 v249, v240, v241
	v_pk_mul_f32 v[242:243], v[14:15], v[234:235]
	v_pk_mul_f32 v[244:245], v[16:17], v[234:235]
	v_pk_mul_f32 v[242:243], v[142:143], v[242:243]
	v_pk_mul_f32 v[244:245], v[144:145], v[244:245]
	v_pk_fma_f32 v[242:243], v[242:243], v[174:175], v[206:207]
	v_pk_fma_f32 v[244:245], v[244:245], v[176:177], v[208:209]
	v_cvt_pk_bf16_f32 v250, v242, v243
	v_cvt_pk_bf16_f32 v251, v244, v245
	global_store_dwordx4 v231, v[248:251], s[70:71] offset:1024
	s_nop 1
	v_pk_mul_f32 v[238:239], v[18:19], v[234:235]
	v_pk_mul_f32 v[240:241], v[20:21], v[234:235]
	v_pk_mul_f32 v[238:239], v[146:147], v[238:239]
	v_pk_mul_f32 v[240:241], v[148:149], v[240:241]
	v_pk_fma_f32 v[238:239], v[238:239], v[178:179], v[210:211]
	v_pk_fma_f32 v[240:241], v[240:241], v[180:181], v[212:213]
	v_cvt_pk_bf16_f32 v248, v238, v239
	v_cvt_pk_bf16_f32 v249, v240, v241
	v_pk_mul_f32 v[242:243], v[22:23], v[234:235]
	v_pk_mul_f32 v[244:245], v[24:25], v[234:235]
	v_pk_mul_f32 v[242:243], v[150:151], v[242:243]
	v_pk_mul_f32 v[244:245], v[152:153], v[244:245]
	v_pk_fma_f32 v[242:243], v[242:243], v[182:183], v[214:215]
	v_pk_fma_f32 v[244:245], v[244:245], v[184:185], v[216:217]
	v_cvt_pk_bf16_f32 v250, v242, v243
	v_cvt_pk_bf16_f32 v251, v244, v245
	global_store_dwordx4 v231, v[248:251], s[70:71] offset:2048
	s_nop 1
	v_pk_mul_f32 v[238:239], v[26:27], v[234:235]
	v_pk_mul_f32 v[240:241], v[28:29], v[234:235]
	v_pk_mul_f32 v[238:239], v[154:155], v[238:239]
	v_pk_mul_f32 v[240:241], v[156:157], v[240:241]
	v_pk_fma_f32 v[238:239], v[238:239], v[186:187], v[218:219]
	v_pk_fma_f32 v[240:241], v[240:241], v[188:189], v[220:221]
	v_cvt_pk_bf16_f32 v248, v238, v239
	v_cvt_pk_bf16_f32 v249, v240, v241
	v_pk_mul_f32 v[242:243], v[30:31], v[234:235]
	v_pk_mul_f32 v[244:245], v[32:33], v[234:235]
	v_pk_mul_f32 v[242:243], v[158:159], v[242:243]
	v_pk_mul_f32 v[244:245], v[160:161], v[244:245]
	v_pk_fma_f32 v[242:243], v[242:243], v[226:227], v[222:223]
	v_pk_fma_f32 v[244:245], v[244:245], v[228:229], v[224:225]
	v_cvt_pk_bf16_f32 v250, v242, v243
	v_cvt_pk_bf16_f32 v251, v244, v245
	global_store_dwordx4 v231, v[248:251], s[70:71] offset:3072
	s_nop 1
	s_waitcnt vmcnt(4)
	v_pk_add_f32 v[34:35], v[34:35], v[98:99]
	v_pk_add_f32 v[36:37], v[36:37], v[100:101]
	v_pk_add_f32 v[38:39], v[38:39], v[102:103]
	v_pk_add_f32 v[40:41], v[40:41], v[104:105]
	v_pk_add_f32 v[42:43], v[42:43], v[106:107]
	v_pk_add_f32 v[44:45], v[44:45], v[108:109]
	v_pk_add_f32 v[46:47], v[46:47], v[110:111]
	v_pk_add_f32 v[48:49], v[48:49], v[112:113]
	v_pk_add_f32 v[50:51], v[50:51], v[114:115]
	v_pk_add_f32 v[52:53], v[52:53], v[116:117]
	v_pk_add_f32 v[54:55], v[54:55], v[118:119]
	v_pk_add_f32 v[56:57], v[56:57], v[120:121]
	v_pk_add_f32 v[58:59], v[58:59], v[122:123]
	v_pk_add_f32 v[60:61], v[60:61], v[124:125]
	v_pk_add_f32 v[62:63], v[62:63], v[126:127]
	v_pk_add_f32 v[64:65], v[64:65], v[128:129]
	v_pk_mul_f32 v[232:233], v[34:35], v[34:35]
	v_pk_fma_f32 v[232:233], v[36:37], v[36:37], v[232:233]
	v_pk_fma_f32 v[232:233], v[38:39], v[38:39], v[232:233]
	v_pk_fma_f32 v[232:233], v[40:41], v[40:41], v[232:233]
	v_pk_fma_f32 v[232:233], v[42:43], v[42:43], v[232:233]
	v_pk_fma_f32 v[232:233], v[44:45], v[44:45], v[232:233]
	v_pk_fma_f32 v[232:233], v[46:47], v[46:47], v[232:233]
	v_pk_fma_f32 v[232:233], v[48:49], v[48:49], v[232:233]
	v_pk_fma_f32 v[232:233], v[50:51], v[50:51], v[232:233]
	v_pk_fma_f32 v[232:233], v[52:53], v[52:53], v[232:233]
	v_pk_fma_f32 v[232:233], v[54:55], v[54:55], v[232:233]
	v_pk_fma_f32 v[232:233], v[56:57], v[56:57], v[232:233]
	v_pk_fma_f32 v[232:233], v[58:59], v[58:59], v[232:233]
	v_pk_fma_f32 v[232:233], v[60:61], v[60:61], v[232:233]
	v_pk_fma_f32 v[232:233], v[62:63], v[62:63], v[232:233]
	v_pk_fma_f32 v[232:233], v[64:65], v[64:65], v[232:233]
	v_add_f32_e32 v232, v232, v233
	s_nop 1
	v_add_f32_dpp v232, v232, v232 quad_perm:[1,0,3,2] row_mask:0xf bank_mask:0xf
	s_nop 1
	v_add_f32_dpp v232, v232, v232 quad_perm:[2,3,0,1] row_mask:0xf bank_mask:0xf
	s_nop 1
	v_add_f32_dpp v232, v232, v232 row_half_mirror row_mask:0xf bank_mask:0xf
	s_nop 1
	v_add_f32_dpp v232, v232, v232 row_mirror row_mask:0xf bank_mask:0xf
	s_nop 1
	v_readlane_b32 s0, v232, 0
	v_readlane_b32 s1, v232, 16
	v_readlane_b32 s68, v232, 32
	v_readlane_b32 s69, v232, 48
	s_nop 3
	v_mov_b32_e32 v234, s0
	v_add_f32_e32 v234, s1, v234
	v_add_f32_e32 v234, s68, v234
	v_add_f32_e32 v234, s69, v234
	v_fmaak_f32 v234, v234, v246, 0x358637bd
	v_rsq_f32_e32 v234, v234
	s_nop 0
	v_mov_b32_e32 v235, v234
	s_add_u32 s70, s22, 50335744
	s_addc_u32 s71, s23, 0
	v_pk_mul_f32 v[238:239], v[34:35], v[234:235]
	v_pk_mul_f32 v[240:241], v[36:37], v[234:235]
	v_pk_mul_f32 v[238:239], v[130:131], v[238:239]
	v_pk_mul_f32 v[240:241], v[132:133], v[240:241]
	v_pk_fma_f32 v[238:239], v[238:239], v[162:163], v[194:195]
	v_pk_fma_f32 v[240:241], v[240:241], v[164:165], v[196:197]
	v_cvt_pk_bf16_f32 v248, v238, v239
	v_cvt_pk_bf16_f32 v249, v240, v241
	v_pk_mul_f32 v[242:243], v[38:39], v[234:235]
	v_pk_mul_f32 v[244:245], v[40:41], v[234:235]
	v_pk_mul_f32 v[242:243], v[134:135], v[242:243]
	v_pk_mul_f32 v[244:245], v[136:137], v[244:245]
	v_pk_fma_f32 v[242:243], v[242:243], v[166:167], v[198:199]
	v_pk_fma_f32 v[244:245], v[244:245], v[168:169], v[200:201]
	v_cvt_pk_bf16_f32 v250, v242, v243
	v_cvt_pk_bf16_f32 v251, v244, v245
	global_store_dwordx4 v231, v[248:251], s[70:71]
	s_nop 1
	v_pk_mul_f32 v[238:239], v[42:43], v[234:235]
	v_pk_mul_f32 v[240:241], v[44:45], v[234:235]
	v_pk_mul_f32 v[238:239], v[138:139], v[238:239]
	v_pk_mul_f32 v[240:241], v[140:141], v[240:241]
	v_pk_fma_f32 v[238:239], v[238:239], v[170:171], v[202:203]
	v_pk_fma_f32 v[240:241], v[240:241], v[172:173], v[204:205]
	v_cvt_pk_bf16_f32 v248, v238, v239
	v_cvt_pk_bf16_f32 v249, v240, v241
	v_pk_mul_f32 v[242:243], v[46:47], v[234:235]
	v_pk_mul_f32 v[244:245], v[48:49], v[234:235]
	v_pk_mul_f32 v[242:243], v[142:143], v[242:243]
	v_pk_mul_f32 v[244:245], v[144:145], v[244:245]
	v_pk_fma_f32 v[242:243], v[242:243], v[174:175], v[206:207]
	v_pk_fma_f32 v[244:245], v[244:245], v[176:177], v[208:209]
	v_cvt_pk_bf16_f32 v250, v242, v243
	v_cvt_pk_bf16_f32 v251, v244, v245
	global_store_dwordx4 v231, v[248:251], s[70:71] offset:1024
	s_nop 1
	v_pk_mul_f32 v[238:239], v[50:51], v[234:235]
	v_pk_mul_f32 v[240:241], v[52:53], v[234:235]
	v_pk_mul_f32 v[238:239], v[146:147], v[238:239]
	v_pk_mul_f32 v[240:241], v[148:149], v[240:241]
	v_pk_fma_f32 v[238:239], v[238:239], v[178:179], v[210:211]
	v_pk_fma_f32 v[240:241], v[240:241], v[180:181], v[212:213]
	v_cvt_pk_bf16_f32 v248, v238, v239
	v_cvt_pk_bf16_f32 v249, v240, v241
	v_pk_mul_f32 v[242:243], v[54:55], v[234:235]
	v_pk_mul_f32 v[244:245], v[56:57], v[234:235]
	v_pk_mul_f32 v[242:243], v[150:151], v[242:243]
	v_pk_mul_f32 v[244:245], v[152:153], v[244:245]
	v_pk_fma_f32 v[242:243], v[242:243], v[182:183], v[214:215]
	v_pk_fma_f32 v[244:245], v[244:245], v[184:185], v[216:217]
	v_cvt_pk_bf16_f32 v250, v242, v243
	v_cvt_pk_bf16_f32 v251, v244, v245
	global_store_dwordx4 v231, v[248:251], s[70:71] offset:2048
	s_nop 1
	v_pk_mul_f32 v[238:239], v[58:59], v[234:235]
	v_pk_mul_f32 v[240:241], v[60:61], v[234:235]
	v_pk_mul_f32 v[238:239], v[154:155], v[238:239]
	v_pk_mul_f32 v[240:241], v[156:157], v[240:241]
	v_pk_fma_f32 v[238:239], v[238:239], v[186:187], v[218:219]
	v_pk_fma_f32 v[240:241], v[240:241], v[188:189], v[220:221]
	v_cvt_pk_bf16_f32 v248, v238, v239
	v_cvt_pk_bf16_f32 v249, v240, v241
	v_pk_mul_f32 v[242:243], v[62:63], v[234:235]
	v_pk_mul_f32 v[244:245], v[64:65], v[234:235]
	v_pk_mul_f32 v[242:243], v[158:159], v[242:243]
	v_pk_mul_f32 v[244:245], v[160:161], v[244:245]
	v_pk_fma_f32 v[242:243], v[242:243], v[226:227], v[222:223]
	v_pk_fma_f32 v[244:245], v[244:245], v[228:229], v[224:225]
	v_cvt_pk_bf16_f32 v250, v242, v243
	v_cvt_pk_bf16_f32 v251, v244, v245
	global_store_dwordx4 v231, v[248:251], s[70:71] offset:3072
	s_nop 1
